# GEMM K-loop: peel first iteration with C=0 MFMAs, drop the 128 accumulator-zeroing moves per tile
# speedup vs baseline: 1.0038x; 1.0038x over previous
; #define PG8_STAGE(bufoff, gbase, voff) do { _Pragma("unroll") for (int _i = 0; _i < 2; ++_i) \
;         __builtin_amdgcn_global_load_lds((const unsigned*)((const char*)(gbase) + (voff)[_i]), (PG8_LAS unsigned*)(lds + (bufoff) + ldsw + _i * 8192), 16, 0, 0); } while (0)
; #define PG8_LDA(dst, b, h) do { _Pragma("unroll") for (int m = 0; m < 4; ++m) _Pragma("unroll") for (int k = 0; k < 2; ++k) dst[m][k] = *(const PG8_LAS bf16x8*)(lds + PG8_SA(b, h) + aoff + m * 2048 + k * 1024); } while (0)
; #define PG8_LDB(dst, b, h) do { _Pragma("unroll") for (int n = 0; n < 2; ++n) _Pragma("unroll") for (int k = 0; k < 2; ++k) dst[n][k] = *(const PG8_LAS bf16x8*)(lds + PG8_SB(b, h) + boff + n * 2048 + k * 1024); } while (0)
; #define PG8_MMA(ai, bj, At, Bt) do { __builtin_amdgcn_s_setprio(1); _Pragma("unroll") for (int m = 0; m < 4; ++m) _Pragma("unroll") for (int n = 0; n < 2; ++n) _Pragma("unroll") for (int k = 0; k < 2; ++k) \
;         acc[ai][bj][m][n] = __builtin_amdgcn_mfma_f32_16x16x32_bf16(Bt[n][k], At[m][k], acc[ai][bj][m][n], 0, 0, 0); __builtin_amdgcn_s_setprio(0); } while (0)
; #define PG8_WAIT_V(n) asm volatile("s_waitcnt vmcnt(" #n ")" ::: "memory")
; #define PG8_WAIT_L(n) asm volatile("s_waitcnt lgkmcnt(" #n ")" ::: "memory")
; template <class Epi, class Sched, bool ALIGN_EPI = false, bool SP2 = false>
; __device__ __forceinline__ void gemm_phase(PG8_LAS unsigned char* lds, const Gemm g, const Sched& S, const Epi& E) {
;     ...
;             const bool last = (t == nt - 2);
;             const char* a1 = cA + (size_t)(t + 1) * kstep;
;             const char* a2 = last ? nA : cA + (size_t)(t + 2) * kstep; const char* b2 = last ? nB : cB + (size_t)(t + 2) * kstep;
;             const char* a3 = a2 + kstep; const char* b3 = b2 + kstep;
;             if (last && has_next) S.a_ready(nxt);
;             if constexpr (SP2) {
;             PG8_LDB(B0, 0, 0); PG8_LDB(B1, 0, 1); PG8_SCHED; PG8_LDA(At, 0, 0); PG8_STAGE(PG8_SA(1, 1), a1 + hstepA, voffA);
;             PG8_WAIT_V(8); PG8_WAIT_L(0); PG8_BAR; PG8_MMA(0, 0, At, B0); PG8_MMA(0, 1, At, B1); PG8_BAR; PG8_SCHED;
;             PG8_LDA(At, 0, 1); PG8_STAGE(PG8_SB(0, 0), b2, voffB); PG8_STAGE(PG8_SB(0, 1), b2 + hstepB, voffB); PG8_STAGE(PG8_SA(0, 0), a2, voffA);
;             PG8_WAIT_V(8); PG8_WAIT_L(0); PG8_BAR; PG8_MMA(1, 0, At, B0); PG8_MMA(1, 1, At, B1); PG8_BAR; PG8_SCHED;
.LBB0_517:
	s_add_u32 s0, s0, 0x80
	s_addc_u32 s1, s1, 0
	s_add_u32 s10, s10, 0x100
	s_addc_u32 s11, s11, 0
	s_mov_b32 s8, 0
	s_add_i32 s12, s8, 2
	s_add_u32 s13, s0, 0x80
	s_addc_u32 s9, s1, 0
	s_add_i32 s33, 0, 0x10000
	s_cmp_eq_u32 s95, s8
	s_cselect_b32 s9, s55, s9
	s_cselect_b32 s8, s54, s13
	s_cselect_b32 s15, s45, s11
	s_cselect_b32 s14, s44, s10
	s_add_i32 s13, 0, 0x14000
	v_add_u32_e32 v140, s33, v226
	v_add_u32_e32 v156, s13, v226
	s_waitcnt lgkmcnt(0)
	ds_read_b128 v[128:131], v140
	ds_read_b128 v[132:135], v140 offset:1024
	ds_read_b128 v[136:139], v140 offset:2048
	ds_read_b128 v[140:143], v140 offset:3072
	ds_read_b128 v[144:147], v156
	ds_read_b128 v[148:151], v156 offset:1024
	ds_read_b128 v[152:155], v156 offset:2048
	ds_read_b128 v[156:159], v156 offset:3072
	v_lshl_add_u64 v[212:213], s[0:1], 0, v[176:177]
	s_add_i32 m0, s79, 0xc000
	ds_read_b128 v[180:183], v227
	ds_read_b128 v[184:187], v227 offset:1024
	ds_read_b128 v[188:191], v227 offset:2048
	ds_read_b128 v[192:195], v227 offset:3072
	ds_read_b128 v[196:199], v227 offset:4096
	ds_read_b128 v[200:203], v227 offset:5120
	ds_read_b128 v[204:207], v227 offset:6144
	ds_read_b128 v[208:211], v227 offset:7168
	global_load_lds_dwordx4 v[212:213], off
	v_lshl_add_u64 v[212:213], s[0:1], 0, v[178:179]
	s_add_i32 m0, s79, 0xe000
	s_nop 0
	global_load_lds_dwordx4 v[212:213], off
	s_waitcnt vmcnt(8)
	s_waitcnt lgkmcnt(0)
	s_barrier
	s_setprio 1
	s_waitcnt lgkmcnt(0)
	v_mfma_f32_16x16x32_bf16 v[124:127], v[128:131], v[180:183], 0
	v_mfma_f32_16x16x32_bf16 v[120:123], v[136:139], v[180:183], 0
	v_mfma_f32_16x16x32_bf16 v[108:111], v[128:131], v[188:191], 0
	v_mfma_f32_16x16x32_bf16 v[104:107], v[136:139], v[188:191], 0
	v_mfma_f32_16x16x32_bf16 v[92:95], v[128:131], v[196:199], 0
	v_mfma_f32_16x16x32_bf16 v[88:91], v[136:139], v[196:199], 0
	v_mfma_f32_16x16x32_bf16 v[76:79], v[128:131], v[204:207], 0
	v_mfma_f32_16x16x32_bf16 v[72:75], v[136:139], v[204:207], 0
	v_mfma_f32_16x16x32_bf16 v[124:127], v[132:135], v[184:187], v[124:127]
	v_mfma_f32_16x16x32_bf16 v[120:123], v[140:143], v[184:187], v[120:123]
	v_mfma_f32_16x16x32_bf16 v[108:111], v[132:135], v[192:195], v[108:111]
	v_mfma_f32_16x16x32_bf16 v[104:107], v[140:143], v[192:195], v[104:107]
	v_mfma_f32_16x16x32_bf16 v[92:95], v[132:135], v[200:203], v[92:95]
	v_mfma_f32_16x16x32_bf16 v[88:91], v[140:143], v[200:203], v[88:91]
	v_mfma_f32_16x16x32_bf16 v[76:79], v[132:135], v[208:211], v[76:79]
	v_mfma_f32_16x16x32_bf16 v[72:75], v[140:143], v[208:211], v[72:75]
	s_setprio 0
	s_setprio 1
	v_mfma_f32_16x16x32_bf16 v[116:119], v[144:147], v[180:183], 0
	v_mfma_f32_16x16x32_bf16 v[112:115], v[152:155], v[180:183], 0
	v_mfma_f32_16x16x32_bf16 v[100:103], v[144:147], v[188:191], 0
	v_mfma_f32_16x16x32_bf16 v[96:99], v[152:155], v[188:191], 0
	v_mfma_f32_16x16x32_bf16 v[84:87], v[144:147], v[196:199], 0
	v_mfma_f32_16x16x32_bf16 v[80:83], v[152:155], v[196:199], 0
	v_mfma_f32_16x16x32_bf16 v[68:71], v[144:147], v[204:207], 0
	v_mfma_f32_16x16x32_bf16 v[64:67], v[152:155], v[204:207], 0
	v_mfma_f32_16x16x32_bf16 v[116:119], v[148:151], v[184:187], v[116:119]
	v_mfma_f32_16x16x32_bf16 v[112:115], v[156:159], v[184:187], v[112:115]
	v_mfma_f32_16x16x32_bf16 v[100:103], v[148:151], v[192:195], v[100:103]
	v_mfma_f32_16x16x32_bf16 v[96:99], v[156:159], v[192:195], v[96:99]
	v_mfma_f32_16x16x32_bf16 v[84:87], v[148:151], v[200:203], v[84:87]
	v_mfma_f32_16x16x32_bf16 v[80:83], v[156:159], v[200:203], v[80:83]
	v_mfma_f32_16x16x32_bf16 v[68:71], v[148:151], v[208:211], v[68:71]
	v_mfma_f32_16x16x32_bf16 v[64:67], v[156:159], v[208:211], v[64:67]
	s_setprio 0
	s_barrier
	s_add_i32 s33, s33, s78
	v_lshl_add_u64 v[212:213], s[14:15], 0, v[170:171]
	s_mov_b32 m0, s33
	ds_read_b128 v[180:183], v227 offset:16384
	ds_read_b128 v[184:187], v227 offset:17408
	ds_read_b128 v[188:191], v227 offset:18432
	ds_read_b128 v[192:195], v227 offset:19456
	ds_read_b128 v[196:199], v227 offset:20480
	ds_read_b128 v[200:203], v227 offset:21504
	ds_read_b128 v[204:207], v227 offset:22528
	ds_read_b128 v[208:211], v227 offset:23552
	global_load_lds_dwordx4 v[212:213], off
	s_add_i32 m0, s33, 0x2000
	v_lshl_add_u64 v[220:221], s[14:15], 0, v[174:175]
	s_add_u32 s14, s14, s38
	s_addc_u32 s15, s15, 0
	s_add_i32 s13, s13, s78
	global_load_lds_dwordx4 v[220:221], off
	v_lshl_add_u64 v[222:223], s[14:15], 0, v[170:171]
	s_mov_b32 m0, s13
	v_lshl_add_u64 v[228:229], s[14:15], 0, v[174:175]
	global_load_lds_dwordx4 v[222:223], off
	s_add_i32 m0, s13, 0x2000
	v_lshl_add_u64 v[230:231], s[8:9], 0, v[168:169]
	global_load_lds_dwordx4 v[228:229], off
	s_mov_b32 m0, s79
	v_lshl_add_u64 v[232:233], s[8:9], 0, v[172:173]
	global_load_lds_dwordx4 v[230:231], off
	s_mov_b32 m0, s82
	s_nop 0
	global_load_lds_dwordx4 v[232:233], off
	s_waitcnt vmcnt(8)
	s_waitcnt lgkmcnt(0)
	s_barrier
; #define PG8_STAGE(bufoff, gbase, voff) do { _Pragma("unroll") for (int _i = 0; _i < 2; ++_i) \
;         __builtin_amdgcn_global_load_lds((const unsigned*)((const char*)(gbase) + (voff)[_i]), (PG8_LAS unsigned*)(lds + (bufoff) + ldsw + _i * 8192), 16, 0, 0); } while (0)
; #define PG8_LDA(dst, b, h) do { _Pragma("unroll") for (int m = 0; m < 4; ++m) _Pragma("unroll") for (int k = 0; k < 2; ++k) dst[m][k] = *(const PG8_LAS bf16x8*)(lds + PG8_SA(b, h) + aoff + m * 2048 + k * 1024); } while (0)
; #define PG8_LDB(dst, b, h) do { _Pragma("unroll") for (int n = 0; n < 2; ++n) _Pragma("unroll") for (int k = 0; k < 2; ++k) dst[n][k] = *(const PG8_LAS bf16x8*)(lds + PG8_SB(b, h) + boff + n * 2048 + k * 1024); } while (0)
; #define PG8_MMA(ai, bj, At, Bt) do { __builtin_amdgcn_s_setprio(1); _Pragma("unroll") for (int m = 0; m < 4; ++m) _Pragma("unroll") for (int n = 0; n < 2; ++n) _Pragma("unroll") for (int k = 0; k < 2; ++k) \
;         acc[ai][bj][m][n] = __builtin_amdgcn_mfma_f32_16x16x32_bf16(Bt[n][k], At[m][k], acc[ai][bj][m][n], 0, 0, 0); __builtin_amdgcn_s_setprio(0); } while (0)
; #define PG8_WAIT_V(n) asm volatile("s_waitcnt vmcnt(" #n ")" ::: "memory")
; #define PG8_WAIT_L(n) asm volatile("s_waitcnt lgkmcnt(" #n ")" ::: "memory")
; #define PG8_BAR __builtin_amdgcn_s_barrier()
; #define PG8_SCHED __builtin_amdgcn_sched_barrier(0)
; template <class Epi, class Sched, bool ALIGN_EPI = false, bool SP2 = false>
; __device__ __forceinline__ void gemm_phase(PG8_LAS unsigned char* lds, const Gemm g, const Sched& S, const Epi& E) {
;     ...
;             PG8_WAIT_V(8); PG8_WAIT_L(0); PG8_BAR; PG8_MMA(1, 0, At, B0); PG8_MMA(1, 1, At, B1); PG8_BAR; PG8_SCHED;
;             PG8_LDB(B0, 1, 0); PG8_LDB(B1, 1, 1); PG8_SCHED; PG8_LDA(At, 1, 0); PG8_STAGE(PG8_SA(0, 1), a2 + hstepA, voffA);
;             PG8_WAIT_V(8); PG8_WAIT_L(0); PG8_BAR; PG8_MMA(0, 0, At, B0); PG8_MMA(0, 1, At, B1); PG8_BAR; PG8_SCHED;
	s_setprio 1
	s_waitcnt lgkmcnt(0)
	v_mfma_f32_16x16x32_bf16 v[60:63], v[128:131], v[180:183], 0
	v_mfma_f32_16x16x32_bf16 v[56:59], v[136:139], v[180:183], 0
	v_mfma_f32_16x16x32_bf16 v[44:47], v[128:131], v[188:191], 0
	v_mfma_f32_16x16x32_bf16 v[40:43], v[136:139], v[188:191], 0
	v_mfma_f32_16x16x32_bf16 v[28:31], v[128:131], v[196:199], 0
	v_mfma_f32_16x16x32_bf16 v[24:27], v[136:139], v[196:199], 0
	v_mfma_f32_16x16x32_bf16 v[12:15], v[128:131], v[204:207], 0
	v_mfma_f32_16x16x32_bf16 v[8:11], v[136:139], v[204:207], 0
	v_mfma_f32_16x16x32_bf16 v[60:63], v[132:135], v[184:187], v[60:63]
	v_mfma_f32_16x16x32_bf16 v[56:59], v[140:143], v[184:187], v[56:59]
	v_mfma_f32_16x16x32_bf16 v[44:47], v[132:135], v[192:195], v[44:47]
	v_mfma_f32_16x16x32_bf16 v[40:43], v[140:143], v[192:195], v[40:43]
	v_mfma_f32_16x16x32_bf16 v[28:31], v[132:135], v[200:203], v[28:31]
	v_mfma_f32_16x16x32_bf16 v[24:27], v[140:143], v[200:203], v[24:27]
	v_mfma_f32_16x16x32_bf16 v[12:15], v[132:135], v[208:211], v[12:15]
	v_mfma_f32_16x16x32_bf16 v[8:11], v[140:143], v[208:211], v[8:11]
	s_setprio 0
	s_setprio 1
	v_mfma_f32_16x16x32_bf16 v[52:55], v[144:147], v[180:183], 0
	v_mfma_f32_16x16x32_bf16 v[48:51], v[152:155], v[180:183], 0
	v_mfma_f32_16x16x32_bf16 v[36:39], v[144:147], v[188:191], 0
	v_mfma_f32_16x16x32_bf16 v[32:35], v[152:155], v[188:191], 0
	v_mfma_f32_16x16x32_bf16 v[20:23], v[144:147], v[196:199], 0
	v_mfma_f32_16x16x32_bf16 v[16:19], v[152:155], v[196:199], 0
	v_mfma_f32_16x16x32_bf16 v[4:7], v[144:147], v[204:207], 0
	v_mfma_f32_16x16x32_bf16 v[0:3], v[152:155], v[204:207], 0
	v_mfma_f32_16x16x32_bf16 v[52:55], v[148:151], v[184:187], v[52:55]
	v_mfma_f32_16x16x32_bf16 v[48:51], v[156:159], v[184:187], v[48:51]
	v_mfma_f32_16x16x32_bf16 v[36:39], v[148:151], v[192:195], v[36:39]
	v_mfma_f32_16x16x32_bf16 v[32:35], v[156:159], v[192:195], v[32:35]
	v_mfma_f32_16x16x32_bf16 v[20:23], v[148:151], v[200:203], v[20:23]
	v_mfma_f32_16x16x32_bf16 v[16:19], v[156:159], v[200:203], v[16:19]
	v_mfma_f32_16x16x32_bf16 v[4:7], v[148:151], v[208:211], v[4:7]
	v_mfma_f32_16x16x32_bf16 v[0:3], v[156:159], v[208:211], v[0:3]
	s_setprio 0
	s_barrier
	s_add_i32 s13, 0, 0x18000
	s_add_i32 s14, 0, 0x1c000
	v_add_u32_e32 v140, s13, v226
	v_add_u32_e32 v156, s14, v226
	ds_read_b128 v[128:131], v140
	ds_read_b128 v[132:135], v140 offset:1024
	ds_read_b128 v[136:139], v140 offset:2048
	ds_read_b128 v[140:143], v140 offset:3072
	ds_read_b128 v[144:147], v156
	ds_read_b128 v[148:151], v156 offset:1024
	ds_read_b128 v[152:155], v156 offset:2048
	ds_read_b128 v[156:159], v156 offset:3072
	s_add_u32 s8, s8, s38
	s_addc_u32 s9, s9, 0
	s_mov_b32 m0, s83
	v_lshl_add_u64 v[234:235], s[8:9], 0, v[168:169]
	ds_read_b128 v[180:183], v227 offset:32768
	ds_read_b128 v[184:187], v227 offset:33792
	ds_read_b128 v[188:191], v227 offset:34816
	ds_read_b128 v[192:195], v227 offset:35840
	ds_read_b128 v[196:199], v227 offset:36864
	ds_read_b128 v[200:203], v227 offset:37888
	ds_read_b128 v[204:207], v227 offset:38912
	ds_read_b128 v[208:211], v227 offset:39936
	global_load_lds_dwordx4 v[234:235], off
	v_lshl_add_u64 v[234:235], s[8:9], 0, v[172:173]
	s_mov_b32 m0, s84
	s_nop 0
	global_load_lds_dwordx4 v[234:235], off
	s_waitcnt vmcnt(8)
	s_waitcnt lgkmcnt(0)
	s_barrier
	s_setprio 1
	s_waitcnt lgkmcnt(0)
	v_mfma_f32_16x16x32_bf16 v[124:127], v[128:131], v[180:183], v[124:127]
	v_mfma_f32_16x16x32_bf16 v[120:123], v[136:139], v[180:183], v[120:123]
	v_mfma_f32_16x16x32_bf16 v[108:111], v[128:131], v[188:191], v[108:111]
	v_mfma_f32_16x16x32_bf16 v[104:107], v[136:139], v[188:191], v[104:107]
	v_mfma_f32_16x16x32_bf16 v[92:95], v[128:131], v[196:199], v[92:95]
	v_mfma_f32_16x16x32_bf16 v[88:91], v[136:139], v[196:199], v[88:91]
	v_mfma_f32_16x16x32_bf16 v[76:79], v[128:131], v[204:207], v[76:79]
	v_mfma_f32_16x16x32_bf16 v[72:75], v[136:139], v[204:207], v[72:75]
	v_mfma_f32_16x16x32_bf16 v[124:127], v[132:135], v[184:187], v[124:127]
	v_mfma_f32_16x16x32_bf16 v[120:123], v[140:143], v[184:187], v[120:123]
	v_mfma_f32_16x16x32_bf16 v[108:111], v[132:135], v[192:195], v[108:111]
	v_mfma_f32_16x16x32_bf16 v[104:107], v[140:143], v[192:195], v[104:107]
	v_mfma_f32_16x16x32_bf16 v[92:95], v[132:135], v[200:203], v[92:95]
	v_mfma_f32_16x16x32_bf16 v[88:91], v[140:143], v[200:203], v[88:91]
	v_mfma_f32_16x16x32_bf16 v[76:79], v[132:135], v[208:211], v[76:79]
	v_mfma_f32_16x16x32_bf16 v[72:75], v[140:143], v[208:211], v[72:75]
	s_setprio 0
	s_setprio 1
	v_mfma_f32_16x16x32_bf16 v[116:119], v[144:147], v[180:183], v[116:119]
	v_mfma_f32_16x16x32_bf16 v[112:115], v[152:155], v[180:183], v[112:115]
	v_mfma_f32_16x16x32_bf16 v[100:103], v[144:147], v[188:191], v[100:103]
	v_mfma_f32_16x16x32_bf16 v[96:99], v[152:155], v[188:191], v[96:99]
	v_mfma_f32_16x16x32_bf16 v[84:87], v[144:147], v[196:199], v[84:87]
	v_mfma_f32_16x16x32_bf16 v[80:83], v[152:155], v[196:199], v[80:83]
	v_mfma_f32_16x16x32_bf16 v[68:71], v[144:147], v[204:207], v[68:71]
	v_mfma_f32_16x16x32_bf16 v[64:67], v[152:155], v[204:207], v[64:67]
	v_mfma_f32_16x16x32_bf16 v[116:119], v[148:151], v[184:187], v[116:119]
	v_mfma_f32_16x16x32_bf16 v[112:115], v[156:159], v[184:187], v[112:115]
	v_mfma_f32_16x16x32_bf16 v[100:103], v[148:151], v[192:195], v[100:103]
	v_mfma_f32_16x16x32_bf16 v[96:99], v[156:159], v[192:195], v[96:99]
	v_mfma_f32_16x16x32_bf16 v[84:87], v[148:151], v[200:203], v[84:87]
	v_mfma_f32_16x16x32_bf16 v[80:83], v[156:159], v[200:203], v[80:83]
	v_mfma_f32_16x16x32_bf16 v[68:71], v[148:151], v[208:211], v[68:71]
	v_mfma_f32_16x16x32_bf16 v[64:67], v[156:159], v[208:211], v[64:67]
	s_setprio 0
	s_barrier
; #define PG8_STAGE(bufoff, gbase, voff) do { _Pragma("unroll") for (int _i = 0; _i < 2; ++_i) \
;         __builtin_amdgcn_global_load_lds((const unsigned*)((const char*)(gbase) + (voff)[_i]), (PG8_LAS unsigned*)(lds + (bufoff) + ldsw + _i * 8192), 16, 0, 0); } while (0)
; #define PG8_LDA(dst, b, h) do { _Pragma("unroll") for (int m = 0; m < 4; ++m) _Pragma("unroll") for (int k = 0; k < 2; ++k) dst[m][k] = *(const PG8_LAS bf16x8*)(lds + PG8_SA(b, h) + aoff + m * 2048 + k * 1024); } while (0)
; #define PG8_MMA(ai, bj, At, Bt) do { __builtin_amdgcn_s_setprio(1); _Pragma("unroll") for (int m = 0; m < 4; ++m) _Pragma("unroll") for (int n = 0; n < 2; ++n) _Pragma("unroll") for (int k = 0; k < 2; ++k) \
;         acc[ai][bj][m][n] = __builtin_amdgcn_mfma_f32_16x16x32_bf16(Bt[n][k], At[m][k], acc[ai][bj][m][n], 0, 0, 0); __builtin_amdgcn_s_setprio(0); } while (0)
; #define PG8_WAIT_V(n) asm volatile("s_waitcnt vmcnt(" #n ")" ::: "memory")
; #define PG8_WAIT_L(n) asm volatile("s_waitcnt lgkmcnt(" #n ")" ::: "memory")
; #define PG8_BAR __builtin_amdgcn_s_barrier()
; #define PG8_SCHED __builtin_amdgcn_sched_barrier(0)
; template <class Epi, class Sched, bool ALIGN_EPI = false, bool SP2 = false>
; __device__ __forceinline__ void gemm_phase(PG8_LAS unsigned char* lds, const Gemm g, const Sched& S, const Epi& E) {
;     ...
;             PG8_LDA(At, 1, 1); PG8_STAGE(PG8_SB(1, 0), b3, voffB); PG8_STAGE(PG8_SB(1, 1), b3 + hstepB, voffB); PG8_STAGE(PG8_SA(1, 0), a3, voffA);
;             PG8_WAIT_V(8); PG8_WAIT_L(0); PG8_BAR; PG8_MMA(1, 0, At, B0); PG8_MMA(1, 1, At, B1); PG8_BAR; PG8_SCHED;
	s_add_i32 s8, s13, s78
	v_lshl_add_u64 v[212:213], v[212:213], 0, s[4:5]
	s_mov_b32 m0, s8
	ds_read_b128 v[180:183], v227 offset:49152
	ds_read_b128 v[184:187], v227 offset:50176
	ds_read_b128 v[188:191], v227 offset:51200
	ds_read_b128 v[192:195], v227 offset:52224
	ds_read_b128 v[196:199], v227 offset:53248
	ds_read_b128 v[200:203], v227 offset:54272
	ds_read_b128 v[204:207], v227 offset:55296
	ds_read_b128 v[208:211], v227 offset:56320
	global_load_lds_dwordx4 v[212:213], off
	v_lshl_add_u64 v[212:213], v[220:221], 0, s[4:5]
	s_add_i32 m0, s8, 0x2000
	s_add_i32 s8, s14, s78
	global_load_lds_dwordx4 v[212:213], off
	v_lshl_add_u64 v[212:213], v[222:223], 0, s[4:5]
	s_mov_b32 m0, s8
	s_nop 0
	global_load_lds_dwordx4 v[212:213], off
	v_lshl_add_u64 v[212:213], v[228:229], 0, s[4:5]
	s_add_i32 m0, s8, 0x2000
	s_nop 0
	global_load_lds_dwordx4 v[212:213], off
	v_lshl_add_u64 v[212:213], v[230:231], 0, s[4:5]
	s_mov_b32 m0, s91
	s_nop 0
	global_load_lds_dwordx4 v[212:213], off
	v_lshl_add_u64 v[212:213], v[232:233], 0, s[4:5]
	s_mov_b32 m0, s94
	s_nop 0
	global_load_lds_dwordx4 v[212:213], off
	s_waitcnt vmcnt(8)
	s_waitcnt lgkmcnt(0)
	s_barrier
	s_setprio 1
	s_waitcnt lgkmcnt(0)
	v_mfma_f32_16x16x32_bf16 v[60:63], v[128:131], v[180:183], v[60:63]
	v_mfma_f32_16x16x32_bf16 v[56:59], v[136:139], v[180:183], v[56:59]
	v_mfma_f32_16x16x32_bf16 v[44:47], v[128:131], v[188:191], v[44:47]
	v_mfma_f32_16x16x32_bf16 v[40:43], v[136:139], v[188:191], v[40:43]
	v_mfma_f32_16x16x32_bf16 v[28:31], v[128:131], v[196:199], v[28:31]
	v_mfma_f32_16x16x32_bf16 v[24:27], v[136:139], v[196:199], v[24:27]
	v_mfma_f32_16x16x32_bf16 v[12:15], v[128:131], v[204:207], v[12:15]
	v_mfma_f32_16x16x32_bf16 v[8:11], v[136:139], v[204:207], v[8:11]
	v_mfma_f32_16x16x32_bf16 v[60:63], v[132:135], v[184:187], v[60:63]
	v_mfma_f32_16x16x32_bf16 v[56:59], v[140:143], v[184:187], v[56:59]
	v_mfma_f32_16x16x32_bf16 v[44:47], v[132:135], v[192:195], v[44:47]
	v_mfma_f32_16x16x32_bf16 v[40:43], v[140:143], v[192:195], v[40:43]
	v_mfma_f32_16x16x32_bf16 v[28:31], v[132:135], v[200:203], v[28:31]
	v_mfma_f32_16x16x32_bf16 v[24:27], v[140:143], v[200:203], v[24:27]
	v_mfma_f32_16x16x32_bf16 v[12:15], v[132:135], v[208:211], v[12:15]
	v_mfma_f32_16x16x32_bf16 v[8:11], v[140:143], v[208:211], v[8:11]
	s_setprio 0
	s_setprio 1
	v_mfma_f32_16x16x32_bf16 v[52:55], v[144:147], v[180:183], v[52:55]
	v_mfma_f32_16x16x32_bf16 v[48:51], v[152:155], v[180:183], v[48:51]
	v_mfma_f32_16x16x32_bf16 v[36:39], v[144:147], v[188:191], v[36:39]
	v_mfma_f32_16x16x32_bf16 v[32:35], v[152:155], v[188:191], v[32:35]
	v_mfma_f32_16x16x32_bf16 v[20:23], v[144:147], v[196:199], v[20:23]
	v_mfma_f32_16x16x32_bf16 v[16:19], v[152:155], v[196:199], v[16:19]
	v_mfma_f32_16x16x32_bf16 v[4:7], v[144:147], v[204:207], v[4:7]
	v_mfma_f32_16x16x32_bf16 v[0:3], v[152:155], v[204:207], v[0:3]
	v_mfma_f32_16x16x32_bf16 v[52:55], v[148:151], v[184:187], v[52:55]
	v_mfma_f32_16x16x32_bf16 v[48:51], v[156:159], v[184:187], v[48:51]
	v_mfma_f32_16x16x32_bf16 v[36:39], v[148:151], v[192:195], v[36:39]
	v_mfma_f32_16x16x32_bf16 v[32:35], v[156:159], v[192:195], v[32:35]
	v_mfma_f32_16x16x32_bf16 v[20:23], v[148:151], v[200:203], v[20:23]
	v_mfma_f32_16x16x32_bf16 v[16:19], v[156:159], v[200:203], v[16:19]
	v_mfma_f32_16x16x32_bf16 v[4:7], v[148:151], v[208:211], v[4:7]
	v_mfma_f32_16x16x32_bf16 v[0:3], v[156:159], v[208:211], v[0:3]
	s_setprio 0
	s_barrier
	s_add_u32 s0, s0, 0x100
	s_addc_u32 s1, s1, 0
	s_add_u32 s10, s10, 0x100
	s_addc_u32 s11, s11, 0
	s_cmp_ge_u32 s12, s86
	s_mov_b32 s8, s12
	s_cbranch_scc1 .Lkloop_done

; #define PG8_BAR __builtin_amdgcn_s_barrier()
; template <class Epi, class Sched, bool ALIGN_EPI = false, bool SP2 = false>
; __device__ __forceinline__ void gemm_phase(PG8_LAS unsigned char* lds, const Gemm g, const Sched& S, const Epi& E) {
;     ...
;         }
;         if constexpr (ALIGN_EPI) { if (wr == 0) PG8_BAR; }
.Lkloop_done:
	s_and_b64 vcc, exec, s[46:47]
	s_cbranch_vccz .LBB0_521
	s_barrier
